# K-order overlap + per-(pm,pn) flags prefetched two K-iterations ahead + FFN-out conversion quota 4608->8064 so 5 FFNs run in overlap mode
# speedup vs baseline: 1.0283x; 1.0108x over previous
.Lko_nog:
	s_cmp_eq_u32 s100, 0
	s_cbranch_scc1 .Lko_nosig
	s_cmp_lt_u32 s62, 4
	s_cbranch_scc1 .Lko_nosig
	s_waitcnt vmcnt(0)
	s_barrier
	s_and_saveexec_b64 s[44:45], s[78:79]
	s_cbranch_execz .Lko_sigdone
	s_load_dwordx2 s[48:49], s[0:1], 0xe0
	buffer_wbl2 sc1
	s_lshl_b32 s4, s101, 6
	s_add_i32 s4, s4, s68
	s_lshl_b32 s4, s4, 2
	s_add_i32 s4, s4, s67
	s_sub_i32 s4, s4, 19
	s_lshl_b32 s4, s4, 2
	s_add_i32 s4, s4, 0x8000
	v_mov_b32_e32 v192, 0
	s_waitcnt vmcnt(0) lgkmcnt(0)
	s_add_u32 s48, s48, s4
	s_addc_u32 s49, s49, 0
	s_nop 4
	global_atomic_add v192, v252, s[48:49]
	s_waitcnt vmcnt(0)

.LBB0_1474:
	s_cmp_eq_u32 s100, 0
	s_cbranch_scc1 .Lko_nopoll
	s_cmp_lt_u32 s82, 34
	s_cbranch_scc1 .Lko_nopoll
	s_cmp_gt_u32 s82, 40
	s_cbranch_scc1 .Lko_nopoll
	s_load_dwordx2 s[90:91], s[0:1], 0xe0
	s_lshl_b32 s4, s101, 6
	s_add_i32 s4, s4, s84
	s_lshl_b32 s4, s4, 4
	s_add_i32 s4, s4, 0x8000
	s_sub_i32 s83, s82, 36
	s_lshl_b32 s83, s83, 1
	s_add_i32 s4, s4, s83
	v_mov_b32_e32 v251, 0
	s_waitcnt lgkmcnt(0)
	s_add_u32 s90, s90, s4
	s_addc_u32 s91, s91, 0
	s_cmp_lt_u32 s82, 36
	s_cbranch_scc1 .Lko_issue
	s_cmp_lg_u32 s82, 36
	s_cbranch_scc1 .Lko_chk
	s_cmp_lt_u32 s84, 8
	s_cbranch_scc1 .Lko_issue
.Lko_chk:
	s_mov_b32 s92, 0
	v_readfirstlane_b32 s83, v248
	s_cmp_lg_u32 s83, 0
	s_cbranch_scc1 .Lko_issue
.Lko_spin:
	s_sleep 8
	global_load_dword v248, v251, s[90:91] sc1
	s_waitcnt vmcnt(0)
	v_readfirstlane_b32 s83, v248
	s_cmp_lg_u32 s83, 0
	s_cbranch_scc1 .Lko_issue
	s_add_i32 s92, s92, 1
	s_cmp_lt_u32 s92, 0x2000
	s_cbranch_scc1 .Lko_spin
.Lko_issue:
	s_cmp_gt_u32 s82, 38
	s_cbranch_scc1 .Lko_nopoll
	s_nop 2
	global_load_dword v248, v251, s[90:91] offset:4 sc1

.LBB0_1539:
	s_and_b64 vcc, exec, s[6:7]
	s_cbranch_vccnz .LBB0_1608
	v_readlane_b32 s6, v253, 18
	v_readlane_b32 s7, v253, 19
	s_andn2_b64 vcc, exec, s[6:7]
	s_cbranch_vccnz .LBB0_1607
	v_mov_b32_e32 v0, v226
	v_readlane_b32 s7, v253, 62
	v_readfirstlane_b32 s4, v0
	v_readlane_b32 s6, v253, 20
	s_ashr_i32 s4, s4, 6
	s_min_i32 s22, s7, 0x7820
	s_add_i32 s6, s6, s7
	s_addk_i32 s22, 0x1f80
	s_waitcnt lgkmcnt(0)
	s_add_i32 s28, s6, s4
	s_cmp_ge_i32 s28, s22
	s_cbranch_scc1 .LBB0_1607
	v_and_b32_e32 v2, 63, v0
	v_bfe_u32 v3, v0, 5, 1
	v_and_b32_e32 v4, 31, v0
	v_bfe_u32 v7, v0, 3, 3
	v_lshlrev_b32_e32 v0, 3, v0
	s_lshl_b32 s4, s4, 14
	v_and_b32_e32 v6, 56, v0
	s_add_i32 s8, s4, 0
	v_mul_u32_u24_e32 v0, 0x84, v6
	v_lshlrev_b32_e32 v9, 2, v7
	v_lshlrev_b32_e32 v8, 2, v4
	v_mul_u32_u24_e32 v5, 0x84, v3
	v_add3_u32 v10, s8, v0, v9
	v_mul_u32_u24_e32 v0, 0x1080, v3
	v_add3_u32 v5, s8, v8, v5
	v_lshl_add_u32 v14, v2, 2, s8
	s_addk_i32 s8, 0x2100
	v_or3_b32 v0, s4, v0, v8
	v_or_b32_e32 v11, 8, v7
	v_or_b32_e32 v12, 16, v7
	v_or_b32_e32 v13, 24, v7
	v_cmp_gt_u32_e64 s[6:7], 32, v2
	v_lshl_add_u32 v15, v3, 7, s8
	v_add_u32_e32 v16, 0, v0
	s_branch .LBB0_1545

.LBB0_1607:
	v_readlane_b32 s4, v253, 62
	s_addk_i32 s4, 0x1f80
	s_nop 0
	v_writelane_b32 v253, s4, 62
